# FFN1 main loop: next stage LDS writes interleaved with the last 6 MFMAs of the stage instead of a serial write pass before the barrier
# baseline (speedup 1.0000x reference)
.Lf1_stageB:
	s_add_i32 s13, s13, 2
	s_waitcnt lgkmcnt(1)
	v_mfma_f32_32x32x16_f16 v[114:129], v[198:201], v[190:193], v[114:129]
	s_waitcnt lgkmcnt(0)
	v_mfma_f32_32x32x16_f16 v[98:113], v[198:201], v[182:185], v[98:113]
	v_mfma_f32_32x32x16_f16 v[82:97], v[194:197], v[190:193], v[82:97]
	v_mfma_f32_32x32x16_f16 v[66:81], v[194:197], v[182:185], v[66:81]
	v_mfma_f32_32x32x16_f16 v[50:65], v[186:189], v[190:193], v[50:65]
	v_mfma_f32_32x32x16_f16 v[34:49], v[186:189], v[182:185], v[34:49]
	v_mfma_f32_32x32x16_f16 v[18:33], v[178:181], v[190:193], v[18:33]
	ds_read_b128 v[186:189], v214 offset:33312
	ds_read_b128 v[190:193], v214 offset:35872
	ds_read_b128 v[194:197], v214 offset:30752
	ds_read_b128 v[198:201], v214 offset:38432
	ds_read_b128 v[216:219], v215 offset:51232
	ds_read_b128 v[220:223], v215 offset:53792
	v_mfma_f32_32x32x16_f16 v[2:17], v[178:181], v[182:185], v[2:17]
	s_and_b64 vcc, exec, s[18:19]
	s_cbranch_vccnz .Lf1_last
	s_cmp_gt_u32 s13, 30
	s_cbranch_scc1 .Lf1_wB0
	s_waitcnt vmcnt(6)
	s_branch .Lf1_wB1

.Lf1_wB1:
	s_waitcnt lgkmcnt(1)
	v_mfma_f32_32x32x16_f16 v[114:129], v[194:197], v[216:219], v[114:129]
	s_waitcnt lgkmcnt(0)
	v_mfma_f32_32x32x16_f16 v[98:113], v[194:197], v[220:223], v[98:113]
	ds_write_b128 v238, v[130:133]
	v_mfma_f32_32x32x16_f16 v[82:97], v[186:189], v[216:219], v[82:97]
	ds_write_b128 v238, v[138:141] offset:5120
	v_mfma_f32_32x32x16_f16 v[66:81], v[186:189], v[220:223], v[66:81]
	ds_write_b128 v238, v[150:153] offset:10240
	v_mfma_f32_32x32x16_f16 v[50:65], v[190:193], v[216:219], v[50:65]
	ds_write_b128 v238, v[162:165] offset:15360
	v_mfma_f32_32x32x16_f16 v[34:49], v[190:193], v[220:223], v[34:49]
	ds_write_b128 v238, v[146:149] offset:20480
	v_mfma_f32_32x32x16_f16 v[18:33], v[198:201], v[216:219], v[18:33]
	ds_write_b128 v238, v[154:157] offset:25600
	v_mfma_f32_32x32x16_f16 v[2:17], v[198:201], v[220:223], v[2:17]
	s_waitcnt lgkmcnt(0)
	s_barrier
.Lf1_stageA:
	ds_read_b128 v[198:201], v214
	ds_read_b128 v[194:197], v214 offset:2560
	ds_read_b128 v[186:189], v214 offset:5120
	ds_read_b128 v[178:181], v214 offset:7680
	ds_read_b128 v[190:193], v215 offset:20480
	ds_read_b128 v[182:185], v215 offset:23040
	s_cmp_gt_u32 s13, 29
	s_cselect_b64 s[18:19], -1, 0
	s_and_b64 vcc, exec, s[18:19]
	s_cbranch_vccnz .Lf1_A2
	v_lshl_add_u64 v[130:131], v[0:1], 1, s[14:15]
	v_lshl_add_u64 v[138:139], v[204:205], 1, s[14:15]
	v_lshl_add_u64 v[146:147], v[206:207], 1, s[14:15]
	global_load_dwordx4 v[130:133], v[130:131], off offset:64
	s_nop 0
	global_load_dwordx4 v[138:141], v[138:139], off offset:64
	v_lshl_add_u64 v[148:149], v[208:209], 1, s[14:15]
	global_load_dwordx4 v[150:153], v[146:147], off offset:64
	global_load_dwordx4 v[162:165], v[148:149], off offset:64
	v_lshl_add_u64 v[146:147], v[210:211], 1, s[16:17]
	v_lshl_add_u64 v[154:155], v[212:213], 1, s[16:17]
	global_load_dwordx4 v[146:149], v[146:147], off offset:64
	s_nop 0
	global_load_dwordx4 v[154:157], v[154:155], off offset:64
	s_add_u32 s14, s14, 64
	s_addc_u32 s15, s15, 0
	s_add_u32 s16, s16, 64
	s_addc_u32 s17, s17, 0
.Lf1_A2:
	s_waitcnt lgkmcnt(1)
	v_mfma_f32_32x32x16_f16 v[114:129], v[198:201], v[190:193], v[114:129]
	s_waitcnt lgkmcnt(0)
	v_mfma_f32_32x32x16_f16 v[98:113], v[198:201], v[182:185], v[98:113]
	v_mfma_f32_32x32x16_f16 v[82:97], v[194:197], v[190:193], v[82:97]
	v_mfma_f32_32x32x16_f16 v[66:81], v[194:197], v[182:185], v[66:81]
	v_mfma_f32_32x32x16_f16 v[50:65], v[186:189], v[190:193], v[50:65]
	v_mfma_f32_32x32x16_f16 v[34:49], v[186:189], v[182:185], v[34:49]
	v_mfma_f32_32x32x16_f16 v[18:33], v[178:181], v[190:193], v[18:33]
	ds_read_b128 v[186:189], v214 offset:32
	ds_read_b128 v[190:193], v214 offset:2592
	ds_read_b128 v[194:197], v214 offset:5152
	ds_read_b128 v[198:201], v214 offset:7712
	ds_read_b128 v[216:219], v215 offset:20512
	ds_read_b128 v[220:223], v215 offset:23072
	v_mfma_f32_32x32x16_f16 v[2:17], v[178:181], v[182:185], v[2:17]
	s_and_b64 vcc, exec, s[18:19]
	s_cbranch_vccnz .Lf1_wA0
	s_waitcnt vmcnt(6)
	s_branch .Lf1_wA1

; template <class BR>
; DI void gemm_tile_w(const h16* __restrict__ A, int lda, const h16* __restrict__ B, int ldb, BR brow, int K, f32x16 (&acc)[4][2], h16* sm) {
;     ...
;   for (int kt = 0; kt < nk; kt += 2) {
;     WIDE_HALF(ra0, rb0, 0, kt)
;     WIDE_HALF(ra1, rb1, 1, kt + 1)
;   }
.Lf1_wA1:
	s_waitcnt lgkmcnt(1)
	v_mfma_f32_32x32x16_f16 v[114:129], v[186:189], v[216:219], v[114:129]
	s_waitcnt lgkmcnt(0)
	v_mfma_f32_32x32x16_f16 v[98:113], v[186:189], v[220:223], v[98:113]
	ds_write_b128 v238, v[134:137] offset:30720
	v_mfma_f32_32x32x16_f16 v[82:97], v[190:193], v[216:219], v[82:97]
	ds_write_b128 v238, v[142:145] offset:35840
	v_mfma_f32_32x32x16_f16 v[66:81], v[190:193], v[220:223], v[66:81]
	ds_write_b128 v238, v[158:161] offset:40960
	v_mfma_f32_32x32x16_f16 v[50:65], v[194:197], v[216:219], v[50:65]
	ds_write_b128 v238, v[166:169] offset:46080
	v_mfma_f32_32x32x16_f16 v[34:49], v[194:197], v[220:223], v[34:49]
	ds_write_b128 v238, v[170:173] offset:51200
	v_mfma_f32_32x32x16_f16 v[18:33], v[198:201], v[216:219], v[18:33]
	ds_write_b128 v238, v[174:177] offset:56320
	v_mfma_f32_32x32x16_f16 v[2:17], v[198:201], v[220:223], v[2:17]
	s_waitcnt lgkmcnt(0)
	s_barrier
	ds_read_b128 v[194:197], v214 offset:33280
	ds_read_b128 v[186:189], v214 offset:35840
	ds_read_b128 v[198:201], v214 offset:30720
	ds_read_b128 v[178:181], v214 offset:38400
	ds_read_b128 v[190:193], v215 offset:51200
	ds_read_b128 v[182:185], v215 offset:53760
	s_cmp_gt_u32 s13, 28
	s_cbranch_scc1 .Lf1_stageB
	v_lshl_add_u64 v[134:135], v[0:1], 1, s[14:15]
	v_lshl_add_u64 v[142:143], v[204:205], 1, s[14:15]
	v_lshl_add_u64 v[158:159], v[206:207], 1, s[14:15]
	v_lshl_add_u64 v[166:167], v[208:209], 1, s[14:15]
	v_lshl_add_u64 v[170:171], v[210:211], 1, s[16:17]
	v_lshl_add_u64 v[174:175], v[212:213], 1, s[16:17]
	global_load_dwordx4 v[134:137], v[134:135], off offset:64
	s_nop 0
	global_load_dwordx4 v[142:145], v[142:143], off offset:64
	s_nop 0
	global_load_dwordx4 v[158:161], v[158:159], off offset:64
	s_nop 0
	global_load_dwordx4 v[166:169], v[166:167], off offset:64
	s_nop 0
	global_load_dwordx4 v[170:173], v[170:171], off offset:64
	s_nop 0
	global_load_dwordx4 v[174:177], v[174:175], off offset:64
	s_add_u32 s14, s14, 64
	s_addc_u32 s15, s15, 0
	s_add_u32 s16, s16, 64
	s_addc_u32 s17, s17, 0
	s_branch .Lf1_stageB
.Lf1_last:
	s_waitcnt lgkmcnt(1)
	v_mfma_f32_32x32x16_f16 v[114:129], v[194:197], v[216:219], v[114:129]
	s_waitcnt lgkmcnt(0)
	v_mfma_f32_32x32x16_f16 v[98:113], v[194:197], v[220:223], v[98:113]
	v_mfma_f32_32x32x16_f16 v[82:97], v[186:189], v[216:219], v[82:97]
	v_mfma_f32_32x32x16_f16 v[66:81], v[186:189], v[220:223], v[66:81]
	v_mfma_f32_32x32x16_f16 v[50:65], v[190:193], v[216:219], v[50:65]
	v_mfma_f32_32x32x16_f16 v[34:49], v[190:193], v[220:223], v[34:49]
	v_mfma_f32_32x32x16_f16 v[18:33], v[198:201], v[216:219], v[18:33]
	v_mfma_f32_32x32x16_f16 v[2:17], v[198:201], v[220:223], v[2:17]
	s_branch .LBB0_69
.Lf1_entry:
	s_waitcnt vmcnt(9)
	ds_write_b128 v238, v[130:133]
	s_waitcnt vmcnt(7)
	ds_write_b128 v238, v[138:141] offset:5120
	s_waitcnt vmcnt(5)
	ds_write_b128 v238, v[150:153] offset:10240
	s_waitcnt vmcnt(3)
	ds_write_b128 v238, v[162:165] offset:15360
	ds_write_b128 v238, v[146:149] offset:20480
	ds_write_b128 v238, v[154:157] offset:25600
	s_waitcnt lgkmcnt(0)
	s_barrier
	s_branch .Lf1_stageA
